# chain loop: prefetch loads retargeted to free VGPRs and issued early; next-step staging interleaved into LDS waits of MFMA phase
# speedup vs baseline: 1.0053x; 1.0053x over previous
.LBB0_500:
	s_andn2_b64 vcc, exec, s[2:3]
	s_cbranch_vccnz .LBB0_505
	s_cmp_gt_u32 s20, 63
	s_cbranch_scc1 .LBB0_505
	s_lshr_b32 s4, s20, 3
	s_bfe_u32 s12, s20, 0x20001
	s_and_b32 s14, s20, 1
	s_bfe_i32 s5, s20, 0x10000
	s_lshl_b32 s15, s4, 2
	s_add_u32 s8, s22, 0x2cbc000
	s_addc_u32 s9, s23, 0
	s_lshl_b32 s2, s12, 2
	s_lshl_b32 s3, s14, 4
	s_or_b32 s2, s3, s2
	s_waitcnt vmcnt(0)
	v_mov_b32_e32 v0, s2
	global_load_dword v1, v0, s[54:55]
	s_mov_b32 s10, 0x3f2aaaab
	v_mov_b32_e32 v16, 0x3ecc95a3
	v_mov_b32_e32 v0, 0x3f317218
	s_mov_b32 s11, 0x3f317218
	s_mov_b32 s13, 0xff800000
	v_mov_b32_e32 v22, 0x7f800000
	v_mov_b32_e32 v23, 0x7fc00000
	v_mov_b32_e32 v24, 0xff800000
	s_mov_b32 s25, 0x33800000
	v_lshrrev_b32_e32 v84, 4, v160
	s_cmp_eq_u32 s14, 0
	v_xor_b32_e32 v25, 0x7f, v84
	s_cselect_b64 s[2:3], -1, 0
	s_lshl_b32 s16, s4, 19
	s_lshl_b32 s17, s14, 18
	s_and_b32 s5, s5, 0xf80
	s_or_b32 s26, s16, s17
	s_add_u32 s16, s8, s26
	s_addc_u32 s17, s9, 0
	s_lshl_b32 s24, s12, 8
	v_and_b32_e32 v99, 15, v160
	s_add_u32 s16, s16, s24
	v_mov_b32_e32 v97, 0
	v_lshlrev_b32_e32 v96, 4, v99
	s_addc_u32 s17, s17, 0
	v_lshlrev_b32_e32 v2, 11, v84
	v_mov_b32_e32 v3, v97
	v_lshl_add_u64 v[4:5], s[16:17], 0, v[96:97]
	v_lshl_add_u64 v[6:7], v[4:5], 0, v[2:3]
	global_load_dwordx4 v[32:35], v[6:7], off
	global_load_dwordx4 v[36:39], v[6:7], off offset:1024
	v_add_u32_e32 v118, 0, v96
	v_bfe_u32 v146, v160, 6, 2
	v_lshrrev_b32_e32 v147, 8, v160
	v_bfe_u32 v64, v160, 2, 2
	v_lshlrev_b32_e32 v148, 3, v84
	v_lshlrev_b32_e32 v149, 7, v147
	v_lshlrev_b32_e32 v151, 6, v146
	v_and_or_b32 v152, v148, 24, v64
	v_mov_b32_e32 v117, v97
	v_mul_u32_u24_e32 v123, 0x130, v84
	s_waitcnt vmcnt(0)
	v_mul_f32_e32 v1, 0x3fb8aa3b, v1
	v_exp_f32_e32 v26, v1
	s_nop 0
	v_sub_f32_e32 v1, 1.0, v26
	v_add_f32_e32 v10, -1.0, v1
	v_frexp_mant_f32_e32 v11, v1
	v_cvt_f64_f32_e32 v[8:9], v1
	v_sub_f32_e32 v12, v10, v1
	v_frexp_exp_i32_f64_e32 v8, v[8:9]
	v_cmp_gt_f32_e32 vcc, s10, v11
	v_sub_f32_e64 v10, -v26, v10
	v_add_f32_e32 v9, 1.0, v12
	v_subbrev_co_u32_e32 v8, vcc, 0, v8, vcc
	v_add_f32_e32 v9, v10, v9
	v_sub_u32_e32 v10, 0, v8
	v_ldexp_f32 v1, v1, v10
	v_ldexp_f32 v9, v9, v10
	v_add_f32_e32 v10, -1.0, v1
	v_add_f32_e32 v12, 1.0, v1
	v_add_f32_e32 v11, 1.0, v10
	v_add_f32_e32 v13, -1.0, v12
	v_sub_f32_e32 v11, v1, v11
	v_sub_f32_e32 v1, v1, v13
	v_add_f32_e32 v1, v9, v1
	v_add_f32_e32 v13, v9, v11
	v_add_f32_e32 v9, v12, v1
	v_rcp_f32_e32 v17, v9
	v_add_f32_e32 v11, v10, v13
	v_sub_f32_e32 v12, v9, v12
	v_sub_f32_e32 v1, v1, v12
	v_mul_f32_e32 v19, v11, v17
	v_mul_f32_e32 v12, v9, v19
	v_fma_f32 v14, v19, v9, -v12
	v_sub_f32_e32 v10, v11, v10
	v_fmac_f32_e32 v14, v19, v1
	v_sub_f32_e32 v18, v13, v10
	v_add_f32_e32 v10, v12, v14
	v_sub_f32_e32 v13, v11, v10
	v_mov_b32_e32 v15, v10
	v_pk_add_f32 v[10:11], v[10:11], v[12:13] neg_lo:[0,1] neg_hi:[0,1]
	v_cvt_f32_i32_e32 v8, v8
	v_pk_add_f32 v[10:11], v[10:11], v[14:15] neg_lo:[0,1] neg_hi:[0,1]
	v_cmp_neq_f32_e32 vcc, s13, v26
	v_add_f32_e32 v11, v18, v11
	v_add_f32_e32 v10, v10, v11
	v_add_f32_e32 v11, v13, v10
	v_mul_f32_e32 v15, v17, v11
	v_mul_f32_e32 v12, v9, v15
	v_fma_f32 v14, v15, v9, -v12
	v_sub_f32_e32 v13, v13, v11
	v_fmac_f32_e32 v14, v15, v1
	v_add_f32_e32 v18, v10, v13
	v_add_f32_e32 v20, v19, v15
	v_add_f32_e32 v10, v12, v14
	v_sub_f32_e32 v9, v20, v19
	v_sub_f32_e32 v13, v11, v10
	v_sub_f32_e32 v1, v15, v9
	v_mov_b32_e32 v15, v10
	v_pk_add_f32 v[10:11], v[10:11], v[12:13] neg_lo:[0,1] neg_hi:[0,1]
	s_nop 0
	v_pk_add_f32 v[10:11], v[10:11], v[14:15] neg_lo:[0,1] neg_hi:[0,1]
	s_nop 0
	v_add_f32_e32 v9, v18, v11
	v_add_f32_e32 v9, v10, v9
	v_add_f32_e32 v9, v13, v9
	v_mul_f32_e32 v9, v17, v9
	v_add_f32_e32 v1, v1, v9
	v_add_f32_e32 v9, v20, v1
	v_mul_f32_e32 v10, v9, v9
	v_sub_f32_e32 v12, v9, v20
	v_fmac_f32_e32 v16, 0x3e9b6dac, v10
	v_ldexp_f32 v11, v9, 1
	v_sub_f32_e32 v12, v1, v12
	v_mul_f32_e32 v9, v9, v10
	v_fmaak_f32 v1, v10, v16, 0x3f2aaada
	v_pk_mul_f32 v[0:1], v[8:9], v[0:1]
	v_ldexp_f32 v13, v12, 1
	v_fma_f32 v9, v8, s11, -v0
	v_fmamk_f32 v10, v8, 0xb102e308, v9
	v_pk_add_f32 v[8:9], v[0:1], v[10:11]
	v_mov_b32_e32 v12, v0
	v_sub_f32_e32 v16, v9, v11
	v_pk_add_f32 v[14:15], v[8:9], v[0:1] neg_lo:[0,1] neg_hi:[0,1]
	v_sub_f32_e32 v1, v1, v16
	v_add_f32_e32 v13, v13, v1
	v_pk_add_f32 v[18:19], v[8:9], v[12:13]
	v_mov_b32_e32 v11, v8
	v_mov_b32_e32 v15, v19
	v_pk_add_f32 v[20:21], v[10:11], v[14:15] neg_lo:[0,1] neg_hi:[0,1]
	v_pk_add_f32 v[10:11], v[10:11], v[14:15]
	v_mov_b32_e32 v0, v9
	v_mov_b32_e32 v17, v8
	v_pk_add_f32 v[8:9], v[10:11], v[8:9] op_sel:[1,0] op_sel_hi:[0,1] neg_lo:[0,1] neg_hi:[0,1]
	v_mov_b32_e32 v16, v13
	v_mov_b32_e32 v12, v19
	v_mov_b32_e32 v13, v11
	v_mov_b32_e32 v1, v8
	v_pk_add_f32 v[14:15], v[18:19], v[8:9] op_sel_hi:[1,0] neg_lo:[0,1] neg_hi:[0,1]
	v_pk_add_f32 v[0:1], v[12:13], v[0:1] neg_lo:[0,1] neg_hi:[0,1]
	v_mov_b32_e32 v14, v20
	v_pk_add_f32 v[0:1], v[16:17], v[0:1] neg_lo:[0,1] neg_hi:[0,1]
	v_mov_b32_e32 v21, v11
	v_pk_add_f32 v[8:9], v[14:15], v[0:1]
	v_cmp_lt_f32_e64 s[10:11], |v26|, s25
	v_pk_add_f32 v[12:13], v[8:9], v[8:9] op_sel:[0,1] op_sel_hi:[1,0]
	s_add_u32 s25, s22, 0x74bc000
	v_pk_add_f32 v[10:11], v[10:11], v[12:13] op_sel:[1,0] op_sel_hi:[0,1]
	v_mov_b32_e32 v9, v10
	v_mov_b32_e32 v1, v12
	v_pk_add_f32 v[12:13], v[8:9], v[20:21] neg_lo:[0,1] neg_hi:[0,1]
	s_addc_u32 s27, s23, 0
	v_sub_f32_e32 v8, v8, v12
	v_pk_add_f32 v[0:1], v[0:1], v[12:13] neg_lo:[0,1] neg_hi:[0,1]
	v_sub_f32_e32 v8, v20, v8
	v_add_f32_e32 v0, v0, v8
	v_add_f32_e32 v0, v0, v1
	v_add_f32_e32 v0, v10, v0
	v_cndmask_b32_e32 v0, v22, v0, vcc
	v_cmp_nlt_f32_e32 vcc, 1.0, v26
	v_sub_u32_e32 v1, 0x5f, v84
	s_xor_b32 s13, s26, 0x40000
	v_cndmask_b32_e32 v0, v23, v0, vcc
	v_cmp_neq_f32_e32 vcc, 1.0, v26
	s_add_u32 s8, s8, s13
	s_addc_u32 s9, s9, 0
	v_cndmask_b32_e32 v0, v24, v0, vcc
	v_cndmask_b32_e64 v8, v0, -v26, s[10:11]
	v_mul_f32_e32 v0, 0x43000000, v8
	v_mul_f32_e32 v0, 0x3fb8aa3b, v0
	v_exp_f32_e32 v98, v0
	v_cndmask_b32_e64 v0, v84, v25, s[2:3]
	v_cvt_f32_ubyte0_e32 v0, v0
	v_mul_f32_e32 v0, v8, v0
	v_mul_f32_e32 v0, 0x3fb8aa3b, v0
	v_exp_f32_e32 v100, v0
	v_add_u32_e32 v0, 32, v84
	v_cndmask_b32_e64 v0, v0, v1, s[2:3]
	v_cvt_f32_ubyte0_e32 v0, v0
	v_mul_f32_e32 v0, v8, v0
	v_mul_f32_e32 v0, 0x3fb8aa3b, v0
	v_exp_f32_e32 v102, v0
	v_or_b32_e32 v0, 64, v84
	v_xor_b32_e32 v1, 63, v84
	s_mov_b32 s10, 0x10000
	v_cndmask_b32_e64 v9, v0, v1, s[2:3]
	v_add_co_u32_e32 v0, vcc, s10, v6
	s_mov_b32 s11, 0x30000
	s_nop 0
	v_addc_co_u32_e32 v1, vcc, 0, v7, vcc
	global_load_dwordx4 v[40:43], v[0:1], off
	global_load_dwordx4 v[44:47], v[0:1], off offset:1024
	v_cvt_f32_ubyte0_e32 v0, v9
	v_sub_u32_e32 v1, 31, v84
	v_mul_f32_e32 v0, v8, v0
	v_cvt_f32_i32_e32 v1, v1
	v_mul_f32_e32 v0, 0x3fb8aa3b, v0
	v_exp_f32_e32 v104, v0
	v_add_u32_e32 v0, 0x60, v84
	v_cvt_f32_ubyte0_e32 v0, v0
	v_cndmask_b32_e64 v0, v0, v1, s[2:3]
	v_mul_f32_e32 v0, v0, v8
	v_mul_f32_e32 v0, 0x3fb8aa3b, v0
	v_exp_f32_e32 v106, v0
	v_or_b32_e32 v0, 0x20000, v2
	v_mov_b32_e32 v1, v97
	v_lshl_add_u64 v[4:5], v[4:5], 0, v[0:1]
	global_load_dwordx4 v[48:51], v[4:5], off
	global_load_dwordx4 v[52:55], v[4:5], off offset:1024
	v_add_co_u32_e32 v4, vcc, s11, v6
	s_add_u32 s8, s8, s24
	s_nop 0
	v_addc_co_u32_e32 v5, vcc, 0, v7, vcc
	global_load_dwordx4 v[56:59], v[4:5], off
	global_load_dwordx4 v[60:63], v[4:5], off offset:1024
	s_addc_u32 s9, s9, 0
	v_lshl_add_u64 v[4:5], s[8:9], 0, v[96:97]
	v_lshl_add_u64 v[2:3], v[4:5], 0, v[2:3]
	v_add_co_u32_e32 v6, vcc, s10, v2
	v_lshl_add_u64 v[0:1], v[4:5], 0, v[0:1]
	s_nop 0
	v_addc_co_u32_e32 v7, vcc, 0, v3, vcc
	global_load_dwordx4 v[28:31], v[2:3], off
	global_load_dwordx4 v[24:27], v[2:3], off offset:1024
	global_load_dwordx4 v[20:23], v[6:7], off
	global_load_dwordx4 v[16:19], v[6:7], off offset:1024
	global_load_dwordx4 v[12:15], v[0:1], off
	global_load_dwordx4 v[8:11], v[0:1], off offset:1024
	v_add_co_u32_e32 v0, vcc, s11, v2
	s_movk_i32 s8, 0x130
	s_nop 0
	v_addc_co_u32_e32 v1, vcc, 0, v3, vcc
	v_mad_u32_u24 v65, v84, s8, v118
	global_load_dwordx4 v[4:7], v[0:1], off
	s_nop 0
	global_load_dwordx4 v[0:3], v[0:1], off offset:1024
	ds_write_b128 v65, v[32:35]
	v_lshlrev_b32_e32 v32, 16, v36
	v_and_b32_e32 v33, 0xffff0000, v36
	v_mov_b32_e32 v101, v100
	v_lshlrev_b32_e32 v34, 16, v37
	v_and_b32_e32 v35, 0xffff0000, v37
	v_pk_mul_f32 v[32:33], v[100:101], v[32:33] op_sel_hi:[0,1]
	v_pk_mul_f32 v[34:35], v[100:101], v[34:35] op_sel_hi:[0,1]
	v_cvt_pk_bf16_f32 v32, v32, v33
	v_cvt_pk_bf16_f32 v33, v34, v35
	v_lshlrev_b32_e32 v34, 16, v38
	v_and_b32_e32 v35, 0xffff0000, v38
	v_lshlrev_b32_e32 v36, 16, v39
	v_and_b32_e32 v37, 0xffff0000, v39
	v_pk_mul_f32 v[34:35], v[100:101], v[34:35] op_sel_hi:[0,1]
	v_pk_mul_f32 v[36:37], v[100:101], v[36:37] op_sel_hi:[0,1]
	v_cvt_pk_bf16_f32 v34, v34, v35
	v_cvt_pk_bf16_f32 v35, v36, v37
	ds_write_b128 v65, v[32:35] offset:38912
	v_mov_b32_e32 v32, 0x2600
	v_mad_u32_u24 v32, v84, s8, v32
	v_add_u32_e32 v119, v118, v32
	v_mov_b32_e32 v103, v102
	v_mov_b32_e32 v105, v104
	v_mov_b32_e32 v107, v106
	s_lshl_b32 s16, s4, 12
	s_or_b32 s4, s5, s16
	s_mulk_i32 s4, 0x1c00
	s_add_u32 s4, s25, s4
	s_addc_u32 s5, s27, 0
	s_add_u32 s4, s4, s24
	s_addc_u32 s5, s5, 0
	s_mov_b64 s[10:11], 0xa8000
	s_mov_b32 s26, 1
	s_mov_b32 s13, 0
	s_waitcnt vmcnt(0)
	ds_write_b128 v119, v[40:43]
	v_lshlrev_b32_e32 v32, 16, v44
	v_and_b32_e32 v33, 0xffff0000, v44
	v_lshlrev_b32_e32 v34, 16, v45
	v_and_b32_e32 v35, 0xffff0000, v45
	v_pk_mul_f32 v[32:33], v[102:103], v[32:33] op_sel_hi:[0,1]
	v_pk_mul_f32 v[34:35], v[102:103], v[34:35] op_sel_hi:[0,1]
	v_cvt_pk_bf16_f32 v32, v32, v33
	v_cvt_pk_bf16_f32 v33, v34, v35
	v_lshlrev_b32_e32 v34, 16, v46
	v_and_b32_e32 v35, 0xffff0000, v46
	v_lshlrev_b32_e32 v36, 16, v47
	v_and_b32_e32 v37, 0xffff0000, v47
	v_pk_mul_f32 v[34:35], v[102:103], v[34:35] op_sel_hi:[0,1]
	v_pk_mul_f32 v[36:37], v[102:103], v[36:37] op_sel_hi:[0,1]
	v_cvt_pk_bf16_f32 v34, v34, v35
	v_cvt_pk_bf16_f32 v35, v36, v37
	ds_write_b128 v119, v[32:35] offset:38912
	ds_write_b128 v119, v[48:51] offset:9728
	v_lshlrev_b32_e32 v32, 16, v52
	v_and_b32_e32 v33, 0xffff0000, v52
	v_lshlrev_b32_e32 v34, 16, v53
	v_and_b32_e32 v35, 0xffff0000, v53
	v_pk_mul_f32 v[32:33], v[104:105], v[32:33] op_sel_hi:[0,1]
	v_pk_mul_f32 v[34:35], v[104:105], v[34:35] op_sel_hi:[0,1]
	v_cvt_pk_bf16_f32 v32, v32, v33
	v_cvt_pk_bf16_f32 v33, v34, v35
	v_lshlrev_b32_e32 v34, 16, v54
	v_and_b32_e32 v35, 0xffff0000, v54
	v_lshlrev_b32_e32 v36, 16, v55
	v_and_b32_e32 v37, 0xffff0000, v55
	v_pk_mul_f32 v[34:35], v[104:105], v[34:35] op_sel_hi:[0,1]
	v_pk_mul_f32 v[36:37], v[104:105], v[36:37] op_sel_hi:[0,1]
	v_cvt_pk_bf16_f32 v34, v34, v35
	v_cvt_pk_bf16_f32 v35, v36, v37
	ds_write_b128 v119, v[32:35] offset:48640
	ds_write_b128 v119, v[56:59] offset:19456
	v_lshlrev_b32_e32 v32, 16, v60
	v_and_b32_e32 v33, 0xffff0000, v60
	v_lshlrev_b32_e32 v34, 16, v61
	v_and_b32_e32 v35, 0xffff0000, v61
	v_pk_mul_f32 v[32:33], v[106:107], v[32:33] op_sel_hi:[0,1]
	v_pk_mul_f32 v[34:35], v[106:107], v[34:35] op_sel_hi:[0,1]
	v_cvt_pk_bf16_f32 v32, v32, v33
	v_cvt_pk_bf16_f32 v33, v34, v35
	v_lshlrev_b32_e32 v34, 16, v62
	v_and_b32_e32 v35, 0xffff0000, v62
	v_lshlrev_b32_e32 v36, 16, v63
	v_and_b32_e32 v37, 0xffff0000, v63
	v_pk_mul_f32 v[34:35], v[106:107], v[34:35] op_sel_hi:[0,1]
	v_pk_mul_f32 v[36:37], v[106:107], v[36:37] op_sel_hi:[0,1]
	v_cvt_pk_bf16_f32 v34, v34, v35
	v_cvt_pk_bf16_f32 v35, v36, v37
	v_lshlrev_b32_e32 v36, 3, v160
	v_and_b32_e32 v150, 24, v36
	ds_write_b128 v119, v[32:35] offset:58368
	v_add3_u32 v120, 0, v149, v150
	v_add3_u32 v121, 0, v151, v150
	s_waitcnt lgkmcnt(0)
	s_barrier
	v_mad_u32_u24 v85, v152, s8, v120
	v_mad_u32_u24 v90, v152, s8, v121
	ds_read_b64_tr_b16 v[38:39], v85 offset:1216
	ds_read_b64_tr_b16 v[36:37], v85
	ds_read_b64_tr_b16 v[40:41], v85 offset:32
	ds_read_b64_tr_b16 v[44:45], v85 offset:64
	ds_read_b64_tr_b16 v[48:49], v85 offset:96
	ds_read_b64_tr_b16 v[54:55], v90 offset:40128
	ds_read_b64_tr_b16 v[52:53], v90 offset:38912
	ds_read_b64_tr_b16 v[42:43], v85 offset:1248
	ds_read_b64_tr_b16 v[46:47], v85 offset:1280
	ds_read_b64_tr_b16 v[50:51], v85 offset:1312
	ds_read_b64_tr_b16 v[58:59], v90 offset:40160
	ds_read_b64_tr_b16 v[56:57], v90 offset:38944
	v_mul_f32_e32 v32, 0, v98
	v_mov_b32_e32 v33, v32
	v_mov_b32_e32 v34, v32
	v_mov_b32_e32 v35, v32
	s_waitcnt lgkmcnt(0)
	s_nop 0
	v_mfma_f32_16x16x32_bf16 v[60:63], v[36:39], v[52:55], v[32:35]
	v_mfma_f32_16x16x32_bf16 v[36:39], v[36:39], v[56:59], v[32:35]
	v_mfma_f32_16x16x32_bf16 v[64:67], v[40:43], v[52:55], v[32:35]
	v_mfma_f32_16x16x32_bf16 v[40:43], v[40:43], v[56:59], v[32:35]
	v_mfma_f32_16x16x32_bf16 v[68:71], v[44:47], v[52:55], v[32:35]
	v_mfma_f32_16x16x32_bf16 v[44:47], v[44:47], v[56:59], v[32:35]
	v_mfma_f32_16x16x32_bf16 v[52:55], v[48:51], v[52:55], v[32:35]
	v_mfma_f32_16x16x32_bf16 v[32:35], v[48:51], v[56:59], v[32:35]
	ds_read_b64_tr_b16 v[50:51], v85 offset:10944
	ds_read_b64_tr_b16 v[48:49], v85 offset:9728
	ds_read_b64_tr_b16 v[56:57], v85 offset:9760
	ds_read_b64_tr_b16 v[72:73], v85 offset:9792
	ds_read_b64_tr_b16 v[76:77], v85 offset:9824
	ds_read_b64_tr_b16 v[80:81], v90 offset:48640
	ds_read_b64_tr_b16 v[82:83], v90 offset:49856
	ds_read_b64_tr_b16 v[58:59], v85 offset:10976
	ds_read_b64_tr_b16 v[74:75], v85 offset:11008
	ds_read_b64_tr_b16 v[78:79], v85 offset:11040
	ds_read_b64_tr_b16 v[88:89], v90 offset:49888
	ds_read_b64_tr_b16 v[86:87], v90 offset:48672
	s_waitcnt lgkmcnt(5)
	v_mfma_f32_16x16x32_bf16 v[60:63], v[48:51], v[80:83], v[60:63]
	s_waitcnt lgkmcnt(0)
	v_mfma_f32_16x16x32_bf16 v[36:39], v[48:51], v[86:89], v[36:39]
	v_mfma_f32_16x16x32_bf16 v[48:51], v[56:59], v[80:83], v[64:67]
	v_mfma_f32_16x16x32_bf16 v[40:43], v[56:59], v[86:89], v[40:43]
	v_mfma_f32_16x16x32_bf16 v[56:59], v[72:75], v[80:83], v[68:71]
	v_mfma_f32_16x16x32_bf16 v[44:47], v[72:75], v[86:89], v[44:47]
	v_mfma_f32_16x16x32_bf16 v[64:67], v[76:79], v[80:83], v[52:55]
	v_mfma_f32_16x16x32_bf16 v[68:71], v[76:79], v[86:89], v[32:35]
	s_nop 2
	ds_read_b64_tr_b16 v[34:35], v85 offset:20672
	ds_read_b64_tr_b16 v[32:33], v85 offset:19456
	ds_read_b64_tr_b16 v[52:53], v85 offset:19488
	ds_read_b64_tr_b16 v[72:73], v85 offset:19520
	ds_read_b64_tr_b16 v[76:77], v85 offset:19552
	ds_read_b64_tr_b16 v[80:81], v90 offset:58368
	ds_read_b64_tr_b16 v[82:83], v90 offset:59584
	ds_read_b64_tr_b16 v[54:55], v85 offset:20704
	ds_read_b64_tr_b16 v[74:75], v85 offset:20736
	ds_read_b64_tr_b16 v[78:79], v85 offset:20768
	ds_read_b64_tr_b16 v[88:89], v90 offset:59616
	ds_read_b64_tr_b16 v[86:87], v90 offset:58400
	s_waitcnt lgkmcnt(5)
	v_mfma_f32_16x16x32_bf16 v[60:63], v[32:35], v[80:83], v[60:63]
	s_waitcnt lgkmcnt(0)
	v_mfma_f32_16x16x32_bf16 v[36:39], v[32:35], v[86:89], v[36:39]
	v_mul_u32_u24_e32 v34, 0xe00, v84
	v_lshl_add_u64 v[32:33], s[4:5], 0, v[96:97]
	v_lshlrev_b32_e32 v116, 1, v34
	v_mfma_f32_16x16x32_bf16 v[108:111], v[52:55], v[86:89], v[40:43]
	v_lshl_add_u64 v[144:145], v[32:33], 0, v[116:117]
	s_mov_b64 s[4:5], 0x38000
	s_nop 0
	v_mov_b32_e32 v40, 0x7200
	v_mad_u32_u24 v40, v152, s8, v40
	v_mfma_f32_16x16x32_bf16 v[48:51], v[52:55], v[80:83], v[48:51]
	global_load_dwordx4 v[202:205], v[144:145], off offset:1024
	global_load_dwordx4 v[206:209], v[144:145], off offset:2048
	v_add_u32_e32 v122, v121, v40
	s_mov_b64 s[8:9], 0x70000
	v_mfma_f32_16x16x32_bf16 v[112:115], v[72:75], v[80:83], v[56:59]
	v_mfma_f32_16x16x32_bf16 v[124:127], v[72:75], v[86:89], v[44:47]
	s_nop 1
	v_lshl_add_u64 v[56:57], v[144:145], 0, s[4:5]
	v_mfma_f32_16x16x32_bf16 v[128:131], v[76:79], v[80:83], v[64:67]
	ds_read_b64_tr_b16 v[42:43], v85 offset:30400
	ds_read_b64_tr_b16 v[40:41], v85 offset:29184
	ds_read_b64_tr_b16 v[44:45], v85 offset:29216
	ds_read_b64_tr_b16 v[80:81], v85 offset:29248
	ds_read_b64_tr_b16 v[132:133], v85 offset:29280
	ds_read_b64_tr_b16 v[138:139], v122 offset:40128
	ds_read_b64_tr_b16 v[136:137], v122 offset:38912
	ds_read_b64_tr_b16 v[46:47], v85 offset:30432
	ds_read_b64_tr_b16 v[82:83], v85 offset:30464
	ds_read_b64_tr_b16 v[134:135], v85 offset:30496
	ds_read_b64_tr_b16 v[142:143], v122 offset:40160
	ds_read_b64_tr_b16 v[140:141], v122 offset:38944
	v_mfma_f32_16x16x32_bf16 v[88:91], v[76:79], v[86:89], v[68:71]
	s_waitcnt lgkmcnt(4)
	v_mfma_f32_16x16x32_bf16 v[68:71], v[44:47], v[136:139], v[48:51]
	s_nop 2
	v_lshl_add_u64 v[48:49], v[144:145], 0, s[8:9]
	v_mfma_f32_16x16x32_bf16 v[92:95], v[40:43], v[136:139], v[60:63]
	s_waitcnt lgkmcnt(0)
	v_mfma_f32_16x16x32_bf16 v[64:67], v[40:43], v[140:143], v[36:39]
	s_nop 2
	global_load_dwordx4 v[210:213], v[56:57], off offset:1024
	global_load_dwordx4 v[214:217], v[56:57], off offset:2048
	global_load_dwordx4 v[218:221], v[48:49], off offset:1024
	s_nop 0
	global_load_dwordx4 v[222:225], v[48:49], off offset:2048
	v_lshl_add_u64 v[48:49], v[144:145], 0, s[10:11]
	v_mfma_f32_16x16x32_bf16 v[72:75], v[44:47], v[140:143], v[108:111]
	global_load_dwordx4 v[226:229], v[48:49], off offset:1024
	s_nop 0
	global_load_dwordx4 v[230:233], v[48:49], off offset:2048
	v_mov_b32_e32 v108, v98
	v_mov_b32_e32 v109, v98
	v_mfma_f32_16x16x32_bf16 v[76:79], v[80:83], v[136:139], v[112:115]
	v_mfma_f32_16x16x32_bf16 v[80:83], v[80:83], v[140:143], v[124:127]
	v_mfma_f32_16x16x32_bf16 v[84:87], v[132:135], v[136:139], v[128:131]
	s_nop 1
	v_mul_u32_u24_e32 v124, 0x130, v152
	v_mfma_f32_16x16x32_bf16 v[88:91], v[132:135], v[140:143], v[88:91]
	s_lshl_b32 s14, s14, 5
	v_and_or_b32 v99, v148, 16, v99
	s_or_b32 s14, s15, s14
	v_lshlrev_b32_e32 v110, 4, v99
	v_mov_b32_e32 v111, v97
	v_lshrrev_b32_e32 v99, 1, v160
	s_add_i32 s17, 0, 0x13000
	s_or_b32 s12, s14, s12
	v_lshl_add_u64 v[110:111], s[22:23], 0, v[110:111]
	v_and_b32_e32 v112, 8, v99
	v_mov_b32_e32 v113, v97
	v_add_u32_e32 v115, s17, v96
	s_add_i32 s28, 0, 0x1c800
	v_add3_u32 v127, s17, v149, v150
	s_lshl_b32 s17, s12, 5
	v_lshl_add_u64 v[110:111], v[110:111], 0, v[112:113]
	s_mov_b64 s[14:15], 0x154bc000
	v_lshl_add_u64 v[110:111], v[110:111], 0, s[14:15]
	v_lshlrev_b32_e32 v99, 10, v147
	s_add_u32 s14, s25, s24
	v_lshl_or_b32 v114, v146, 12, v99
	s_addc_u32 s15, s27, 0
	v_add_u32_e32 v126, s28, v96
	v_add3_u32 v128, s28, v151, v150
	v_add_u32_e32 v130, 0x900, v114
	v_add_u32_e32 v132, 0xb00, v114
	v_lshl_add_u64 v[112:113], s[14:15], 0, v[96:97]
	v_lshl_add_u64 v[112:113], v[112:113], 0, v[116:117]
	s_mov_b32 s24, 30
	v_add_u32_e32 v125, v115, v123
	v_add_u32_e32 v126, v126, v123
	v_add_u32_e32 v127, v127, v124
	v_add_u32_e32 v128, v128, v124
	v_lshlrev_b32_e32 v96, 1, v114
	s_movk_i32 s25, 0x1000
	v_lshlrev_b32_e32 v114, 1, v130
	v_lshlrev_b32_e32 v116, 1, v132
	v_mov_b32_e32 v129, 0x1c00
	v_lshlrev_b32_e32 v242, 16, v24
	v_and_b32_e32 v243, 0xffff0000, v24
	v_lshlrev_b32_e32 v244, 16, v25
	v_and_b32_e32 v245, 0xffff0000, v25
	v_lshlrev_b32_e32 v246, 16, v26
	v_and_b32_e32 v247, 0xffff0000, v26
	v_lshlrev_b32_e32 v248, 16, v27
	v_and_b32_e32 v249, 0xffff0000, v27
	v_pk_mul_f32 v[242:243], v[100:101], v[242:243]
	v_pk_mul_f32 v[244:245], v[100:101], v[244:245]
	v_pk_mul_f32 v[246:247], v[100:101], v[246:247]
	v_pk_mul_f32 v[248:249], v[100:101], v[248:249]
	v_cvt_pk_bf16_f32 v24, v242, v243
	v_cvt_pk_bf16_f32 v25, v244, v245
	v_cvt_pk_bf16_f32 v26, v246, v247
	v_cvt_pk_bf16_f32 v27, v248, v249
	ds_write_b128 v125, v[28:31]
	ds_write_b128 v126, v[24:27]
	v_lshlrev_b32_e32 v242, 16, v16
	v_and_b32_e32 v243, 0xffff0000, v16
	v_lshlrev_b32_e32 v244, 16, v17
	v_and_b32_e32 v245, 0xffff0000, v17
	v_lshlrev_b32_e32 v246, 16, v18
	v_and_b32_e32 v247, 0xffff0000, v18
	v_lshlrev_b32_e32 v248, 16, v19
	v_and_b32_e32 v249, 0xffff0000, v19
	v_pk_mul_f32 v[242:243], v[102:103], v[242:243]
	v_pk_mul_f32 v[244:245], v[102:103], v[244:245]
	v_pk_mul_f32 v[246:247], v[102:103], v[246:247]
	v_pk_mul_f32 v[248:249], v[102:103], v[248:249]
	v_cvt_pk_bf16_f32 v16, v242, v243
	v_cvt_pk_bf16_f32 v17, v244, v245
	v_cvt_pk_bf16_f32 v18, v246, v247
	v_cvt_pk_bf16_f32 v19, v248, v249
	ds_write_b128 v125, v[20:23] offset:9728
	ds_write_b128 v126, v[16:19] offset:9728
	v_lshlrev_b32_e32 v242, 16, v8
	v_and_b32_e32 v243, 0xffff0000, v8
	v_lshlrev_b32_e32 v244, 16, v9
	v_and_b32_e32 v245, 0xffff0000, v9
	v_lshlrev_b32_e32 v246, 16, v10
	v_and_b32_e32 v247, 0xffff0000, v10
	v_lshlrev_b32_e32 v248, 16, v11
	v_and_b32_e32 v249, 0xffff0000, v11
	v_pk_mul_f32 v[242:243], v[104:105], v[242:243]
	v_pk_mul_f32 v[244:245], v[104:105], v[244:245]
	v_pk_mul_f32 v[246:247], v[104:105], v[246:247]
	v_pk_mul_f32 v[248:249], v[104:105], v[248:249]
	v_cvt_pk_bf16_f32 v8, v242, v243
	v_cvt_pk_bf16_f32 v9, v244, v245
	v_cvt_pk_bf16_f32 v10, v246, v247
	v_cvt_pk_bf16_f32 v11, v248, v249
	ds_write_b128 v125, v[12:15] offset:19456
	ds_write_b128 v126, v[8:11] offset:19456
	v_lshlrev_b32_e32 v242, 16, v0
	v_and_b32_e32 v243, 0xffff0000, v0
	v_lshlrev_b32_e32 v244, 16, v1
	v_and_b32_e32 v245, 0xffff0000, v1
	v_lshlrev_b32_e32 v246, 16, v2
	v_and_b32_e32 v247, 0xffff0000, v2
	v_lshlrev_b32_e32 v248, 16, v3
	v_and_b32_e32 v249, 0xffff0000, v3
	v_pk_mul_f32 v[242:243], v[106:107], v[242:243]
	v_pk_mul_f32 v[244:245], v[106:107], v[244:245]
	v_pk_mul_f32 v[246:247], v[106:107], v[246:247]
	v_pk_mul_f32 v[248:249], v[106:107], v[248:249]
	v_cvt_pk_bf16_f32 v0, v242, v243
	v_cvt_pk_bf16_f32 v1, v244, v245
	v_cvt_pk_bf16_f32 v2, v246, v247
	v_cvt_pk_bf16_f32 v3, v248, v249
	ds_write_b128 v125, v[4:7] offset:29184
	ds_write_b128 v126, v[0:3] offset:29184
	s_waitcnt vmcnt(0)
.LBB0_503:
	v_pk_mul_f32 v[0:1], v[108:109], v[92:93]
	v_pk_mul_f32 v[4:5], v[108:109], v[64:65]
	v_pk_mul_f32 v[8:9], v[108:109], v[68:69]
	v_mov_b32_e32 v99, v98
	s_waitcnt lgkmcnt(0)
	s_barrier
	v_pk_mul_f32 v[2:3], v[98:99], v[94:95]
	ds_read_b64_tr_b16 v[12:13], v127 offset:1216
	ds_read_b64_tr_b16 v[10:11], v127
	ds_read_b64_tr_b16 v[14:15], v127 offset:32
	ds_read_b64_tr_b16 v[18:19], v127 offset:64
	ds_read_b64_tr_b16 v[22:23], v127 offset:96
	ds_read_b64_tr_b16 v[28:29], v128 offset:1216
	ds_read_b64_tr_b16 v[26:27], v128
	ds_read_b64_tr_b16 v[16:17], v127 offset:1248
	ds_read_b64_tr_b16 v[20:21], v127 offset:1280
	ds_read_b64_tr_b16 v[24:25], v127 offset:1312
	ds_read_b64_tr_b16 v[94:95], v128 offset:1248
	ds_read_b64_tr_b16 v[92:93], v128 offset:32
	v_pk_mul_f32 v[6:7], v[98:99], v[66:67]
	s_waitcnt lgkmcnt(5)
	v_mfma_f32_16x16x32_bf16 v[0:3], v[10:13], v[26:29], v[0:3]
	v_mul_f32_e64 v64, v108, v72
	v_mul_f32_e64 v65, v109, v73
	v_pk_mul_f32 v[66:67], v[98:99], v[74:75]
	v_pk_mul_f32 v[68:69], v[108:109], v[76:77]
	s_waitcnt lgkmcnt(0)
	v_mfma_f32_16x16x32_bf16 v[4:7], v[10:13], v[92:95], v[4:7]
	v_mul_f32_e64 v10, v98, v70
	v_mul_f32_e64 v11, v99, v71
	v_pk_mul_f32 v[12:13], v[108:109], v[80:81]
	v_pk_mul_f32 v[72:73], v[108:109], v[84:85]
	v_mfma_f32_16x16x32_bf16 v[8:11], v[14:17], v[26:29], v[8:11]
	v_mul_f32_e64 v76, v108, v88
	v_mul_f32_e64 v77, v109, v89
	v_pk_mul_f32 v[70:71], v[98:99], v[78:79]
	v_pk_mul_f32 v[74:75], v[98:99], v[86:87]
	v_mfma_f32_16x16x32_bf16 v[64:67], v[14:17], v[92:95], v[64:67]
	v_mul_f32_e64 v14, v98, v82
	v_mul_f32_e64 v15, v99, v83
	v_pk_mul_f32 v[78:79], v[98:99], v[90:91]
	ds_read_b64_tr_b16 v[16:17], v127 offset:9728
	ds_read_b64_tr_b16 v[80:81], v127 offset:9760
	ds_read_b64_tr_b16 v[84:85], v127 offset:9792
	v_mfma_f32_16x16x32_bf16 v[68:71], v[18:21], v[26:29], v[68:71]
	s_add_i32 s27, s26, 2
	s_cmp_lt_u32 s26, 31
	s_cselect_b64 s[14:15], -1, 0
	v_mfma_f32_16x16x32_bf16 v[12:15], v[18:21], v[92:95], v[12:15]
	ds_read_b64_tr_b16 v[18:19], v127 offset:10944
	ds_read_b64_tr_b16 v[82:83], v127 offset:10976
	ds_read_b64_tr_b16 v[86:87], v127 offset:11008
	s_and_b64 s[28:29], s[14:15], exec
	s_cselect_b32 s12, s27, 32
	v_mfma_f32_16x16x32_bf16 v[26:29], v[22:25], v[26:29], v[72:75]
	ds_read_b64_tr_b16 v[20:21], v127 offset:9824
	s_nop 1
	ds_read_b64_tr_b16 v[72:73], v128 offset:9728
	ds_read_b64_tr_b16 v[74:75], v128 offset:10944
	s_add_i32 s30, s12, -2
	s_sub_i32 s12, 33, s12
	v_mfma_f32_16x16x32_bf16 v[76:79], v[22:25], v[92:95], v[76:79]
	ds_read_b64_tr_b16 v[22:23], v127 offset:11040
	ds_read_b64_tr_b16 v[90:91], v128 offset:10976
	ds_read_b64_tr_b16 v[88:89], v128 offset:9760
	s_and_b64 s[28:29], s[2:3], exec
	s_cselect_b32 s12, s30, s12
	s_waitcnt lgkmcnt(3)
	v_mfma_f32_16x16x32_bf16 v[0:3], v[16:19], v[72:75], v[0:3]
	s_lshl_b32 s12, s12, 7
	s_add_i32 s12, s12, s16
	v_mad_i64_i32 v[234:235], s[28:29], s12, v129, v[112:113]
	v_lshl_add_u64 v[236:237], v[234:235], 0, s[4:5]
	v_lshl_add_u64 v[238:239], v[234:235], 0, s[8:9]
	v_lshl_add_u64 v[252:253], v[234:235], 0, s[10:11]
	global_load_dwordx4 v[170:173], v[234:235], off offset:1024
	global_load_dwordx4 v[174:177], v[234:235], off offset:2048
	global_load_dwordx4 v[178:181], v[236:237], off offset:1024
	global_load_dwordx4 v[182:185], v[236:237], off offset:2048
	global_load_dwordx4 v[186:189], v[238:239], off offset:1024
	global_load_dwordx4 v[190:193], v[238:239], off offset:2048
	global_load_dwordx4 v[194:197], v[252:253], off offset:1024
	global_load_dwordx4 v[198:201], v[252:253], off offset:2048
	s_add_i32 s30, s24, 1
	s_waitcnt vmcnt(22)
	v_add_u32_e32 v250, v118, v123
	v_lshlrev_b32_e32 v242, 16, v206
	v_and_b32_e32 v243, 0xffff0000, v206
	v_lshlrev_b32_e32 v244, 16, v207
	v_and_b32_e32 v245, 0xffff0000, v207
	v_lshlrev_b32_e32 v246, 16, v208
	v_and_b32_e32 v247, 0xffff0000, v208
	v_lshlrev_b32_e32 v248, 16, v209
	v_and_b32_e32 v249, 0xffff0000, v209
	v_pk_mul_f32 v[242:243], v[100:101], v[242:243]
	v_pk_mul_f32 v[244:245], v[100:101], v[244:245]
	v_pk_mul_f32 v[246:247], v[100:101], v[246:247]
	v_pk_mul_f32 v[248:249], v[100:101], v[248:249]
	v_cvt_pk_bf16_f32 v206, v242, v243
	v_cvt_pk_bf16_f32 v207, v244, v245
	v_cvt_pk_bf16_f32 v208, v246, v247
	v_cvt_pk_bf16_f32 v209, v248, v249
	ds_write_b128 v250, v[202:205]
	ds_write_b128 v250, v[206:209] offset:38912
	s_waitcnt lgkmcnt(2)
	v_mfma_f32_16x16x32_bf16 v[4:7], v[16:19], v[88:91], v[4:7]
	v_mov_b32_e32 v115, v97
	v_mov_b32_e32 v117, v97
	v_mfma_f32_16x16x32_bf16 v[16:19], v[80:83], v[88:91], v[64:67]
	s_nop 2
	ds_read_b64_tr_b16 v[64:65], v127 offset:19456
	v_mfma_f32_16x16x32_bf16 v[8:11], v[80:83], v[72:75], v[8:11]
	ds_read_b64_tr_b16 v[66:67], v127 offset:20672
	ds_read_b64_tr_b16 v[82:83], v127 offset:20704
	ds_read_b64_tr_b16 v[94:95], v127 offset:20736
	v_mfma_f32_16x16x32_bf16 v[68:71], v[84:87], v[72:75], v[68:71]
	v_mfma_f32_16x16x32_bf16 v[12:15], v[84:87], v[88:91], v[12:15]
	ds_read_b64_tr_b16 v[80:81], v127 offset:19488
	ds_read_b64_tr_b16 v[92:93], v127 offset:19520
	ds_read_b64_tr_b16 v[84:85], v127 offset:19552
	v_mfma_f32_16x16x32_bf16 v[24:27], v[20:23], v[72:75], v[26:29]
	ds_read_b64_tr_b16 v[86:87], v127 offset:20768
	ds_read_b64_tr_b16 v[72:73], v128 offset:19456
	ds_read_b64_tr_b16 v[74:75], v128 offset:20672
	v_mfma_f32_16x16x32_bf16 v[20:23], v[20:23], v[88:91], v[76:79]
	s_nop 2
	ds_read_b64_tr_b16 v[78:79], v128 offset:20704
	ds_read_b64_tr_b16 v[76:77], v128 offset:19488
	ds_read_b64_tr_b16 v[88:89], v127 offset:29184
	ds_read_b64_tr_b16 v[90:91], v127 offset:30400
	ds_read_b64_tr_b16 v[132:133], v127 offset:30432
	ds_read_b64_tr_b16 v[136:137], v127 offset:30464
	ds_read_b64_tr_b16 v[130:131], v127 offset:29216
	ds_read_b64_tr_b16 v[134:135], v127 offset:29248
	ds_read_b64_tr_b16 v[138:139], v127 offset:29280
	ds_read_b64_tr_b16 v[140:141], v127 offset:30496
	ds_read_b64_tr_b16 v[146:147], v128 offset:29184
	ds_read_b64_tr_b16 v[148:149], v128 offset:30400
	s_waitcnt vmcnt(20)
	v_lshlrev_b32_e32 v242, 16, v214
	v_and_b32_e32 v243, 0xffff0000, v214
	v_lshlrev_b32_e32 v244, 16, v215
	v_and_b32_e32 v245, 0xffff0000, v215
	v_lshlrev_b32_e32 v246, 16, v216
	v_and_b32_e32 v247, 0xffff0000, v216
	v_lshlrev_b32_e32 v248, 16, v217
	v_and_b32_e32 v249, 0xffff0000, v217
	v_pk_mul_f32 v[242:243], v[102:103], v[242:243]
	v_pk_mul_f32 v[244:245], v[102:103], v[244:245]
	v_pk_mul_f32 v[246:247], v[102:103], v[246:247]
	v_pk_mul_f32 v[248:249], v[102:103], v[248:249]
	v_cvt_pk_bf16_f32 v214, v242, v243
	v_cvt_pk_bf16_f32 v215, v244, v245
	v_cvt_pk_bf16_f32 v216, v246, v247
	v_cvt_pk_bf16_f32 v217, v248, v249
	ds_write_b128 v250, v[210:213] offset:9728
	ds_write_b128 v250, v[214:217] offset:48640
	s_waitcnt lgkmcnt(14)
	v_mfma_f32_16x16x32_bf16 v[0:3], v[64:67], v[72:75], v[0:3]
	ds_read_b64_tr_b16 v[152:153], v128 offset:30432
	ds_read_b64_tr_b16 v[150:151], v128 offset:29216
	s_waitcnt lgkmcnt(12)
	v_mfma_f32_16x16x32_bf16 v[64:67], v[64:67], v[76:79], v[4:7]
	s_nop 2
	v_mfma_f32_16x16x32_bf16 v[142:145], v[80:83], v[72:75], v[8:11]
	s_add_i32 s12, s26, -1
	v_mfma_f32_16x16x32_bf16 v[80:83], v[80:83], v[76:79], v[16:19]
	s_and_b64 s[28:29], s[2:3], exec
	s_cselect_b32 s12, s12, s30
	s_add_i32 s12, s12, s17
	v_mfma_f32_16x16x32_bf16 v[154:157], v[92:95], v[72:75], v[68:71]
	s_lshl_b64 s[28:29], s[12:13], 15
	v_mfma_f32_16x16x32_bf16 v[162:165], v[92:95], v[76:79], v[12:15]
	s_nop 0
	v_mfma_f32_16x16x32_bf16 v[166:169], v[84:87], v[72:75], v[24:27]
	s_nop 2
	v_mfma_f32_16x16x32_bf16 v[84:87], v[84:87], v[76:79], v[20:23]
	s_nop 2
	s_nop 0
	s_nop 0
	s_waitcnt vmcnt(18)
	v_lshlrev_b32_e32 v242, 16, v222
	v_and_b32_e32 v243, 0xffff0000, v222
	v_lshlrev_b32_e32 v244, 16, v223
	v_and_b32_e32 v245, 0xffff0000, v223
	v_lshlrev_b32_e32 v246, 16, v224
	v_and_b32_e32 v247, 0xffff0000, v224
	v_lshlrev_b32_e32 v248, 16, v225
	v_and_b32_e32 v249, 0xffff0000, v225
	v_pk_mul_f32 v[242:243], v[104:105], v[242:243]
	v_pk_mul_f32 v[244:245], v[104:105], v[244:245]
	v_pk_mul_f32 v[246:247], v[104:105], v[246:247]
	v_pk_mul_f32 v[248:249], v[104:105], v[248:249]
	v_cvt_pk_bf16_f32 v222, v242, v243
	v_cvt_pk_bf16_f32 v223, v244, v245
	v_cvt_pk_bf16_f32 v224, v246, v247
	v_cvt_pk_bf16_f32 v225, v248, v249
	ds_write_b128 v250, v[218:221] offset:19456
	ds_write_b128 v250, v[222:225] offset:58368
	s_waitcnt lgkmcnt(4)
	v_mfma_f32_16x16x32_bf16 v[92:95], v[88:91], v[146:149], v[0:3]
	s_nop 2
	s_waitcnt vmcnt(16)
	v_lshlrev_b32_e32 v242, 16, v230
	v_and_b32_e32 v243, 0xffff0000, v230
	v_lshlrev_b32_e32 v244, 16, v231
	v_and_b32_e32 v245, 0xffff0000, v231
	v_lshlrev_b32_e32 v246, 16, v232
	v_and_b32_e32 v247, 0xffff0000, v232
	v_lshlrev_b32_e32 v248, 16, v233
	v_and_b32_e32 v249, 0xffff0000, v233
	v_pk_mul_f32 v[242:243], v[106:107], v[242:243]
	v_pk_mul_f32 v[244:245], v[106:107], v[244:245]
	v_pk_mul_f32 v[246:247], v[106:107], v[246:247]
	v_pk_mul_f32 v[248:249], v[106:107], v[248:249]
	v_cvt_pk_bf16_f32 v230, v242, v243
	v_cvt_pk_bf16_f32 v231, v244, v245
	v_cvt_pk_bf16_f32 v232, v246, v247
	v_cvt_pk_bf16_f32 v233, v248, v249
	ds_write_b128 v250, v[226:229] offset:29184
	ds_write_b128 v119, v[230:233] offset:58368
	s_waitcnt lgkmcnt(2)
	v_mfma_f32_16x16x32_bf16 v[68:71], v[130:133], v[150:153], v[80:83]
	s_nop 2
	v_lshl_add_u64 v[80:81], v[110:111], 0, s[28:29]
	v_mfma_f32_16x16x32_bf16 v[88:91], v[88:91], v[150:153], v[64:67]
	v_mfma_f32_16x16x32_bf16 v[64:67], v[130:133], v[146:149], v[142:145]
	v_lshl_add_u64 v[130:131], v[80:81], 0, v[96:97]
	v_lshl_add_u64 v[132:133], v[80:81], 0, v[114:115]
	v_mfma_f32_16x16x32_bf16 v[72:75], v[134:137], v[146:149], v[154:157]
	v_cvt_pk_bf16_f32 v144, v68, v69
	s_nop 3
	v_cvt_pk_bf16_f32 v142, v64, v65
	v_cvt_pk_bf16_f32 v143, v66, v67
	v_mfma_f32_16x16x32_bf16 v[76:79], v[134:137], v[150:153], v[162:165]
	v_lshl_add_u64 v[134:135], v[80:81], 0, v[116:117]
	v_add_co_u32_e32 v136, vcc, s25, v130
	v_mfma_f32_16x16x32_bf16 v[80:83], v[138:141], v[146:149], v[166:169]
	s_nop 0
	v_addc_co_u32_e32 v137, vcc, 0, v131, vcc
	v_cvt_pk_bf16_f32 v145, v70, v71
	v_mfma_f32_16x16x32_bf16 v[84:87], v[138:141], v[150:153], v[84:87]
	v_cvt_pk_bf16_f32 v138, v92, v93
	v_cvt_pk_bf16_f32 v139, v94, v95
	v_cvt_pk_bf16_f32 v140, v88, v89
	v_cvt_pk_bf16_f32 v141, v90, v91
	v_cvt_pk_bf16_f32 v146, v72, v73
	v_cvt_pk_bf16_f32 v147, v74, v75
	v_cvt_pk_bf16_f32 v148, v76, v77
	v_cvt_pk_bf16_f32 v149, v78, v79
	v_cvt_pk_bf16_f32 v150, v80, v81
	v_cvt_pk_bf16_f32 v151, v82, v83
	v_cvt_pk_bf16_f32 v152, v84, v85
	v_cvt_pk_bf16_f32 v153, v86, v87
	global_store_dwordx2 v[130:131], v[138:139], off
	global_store_dwordx2 v[136:137], v[140:141], off
	global_store_dwordx2 v[130:131], v[142:143], off offset:512
	global_store_dwordx2 v[132:133], v[144:145], off
	global_store_dwordx2 v[130:131], v[146:147], off offset:1024
	global_store_dwordx2 v[136:137], v[148:149], off offset:1024
	global_store_dwordx2 v[130:131], v[150:151], off offset:1536
	global_store_dwordx2 v[134:135], v[152:153], off
	v_pk_mul_f32 v[54:55], v[98:99], v[90:91]
	v_pk_mul_f32 v[52:53], v[108:109], v[88:89]
	v_pk_mul_f32 v[50:51], v[98:99], v[94:95]
	v_pk_mul_f32 v[48:49], v[108:109], v[92:93]
	v_add_u32_e32 v155, v120, v124
	s_waitcnt lgkmcnt(0)
	s_barrier
	v_add_u32_e32 v156, v121, v124
	ds_read_b64_tr_b16 v[34:35], v155 offset:1216
	ds_read_b64_tr_b16 v[32:33], v155
	ds_read_b64_tr_b16 v[36:37], v155 offset:32
	ds_read_b64_tr_b16 v[40:41], v155 offset:64
	ds_read_b64_tr_b16 v[44:45], v155 offset:96
	ds_read_b64_tr_b16 v[58:59], v156 offset:40128
	ds_read_b64_tr_b16 v[56:57], v156 offset:38912
	ds_read_b64_tr_b16 v[38:39], v155 offset:1248
	ds_read_b64_tr_b16 v[42:43], v155 offset:1280
	ds_read_b64_tr_b16 v[46:47], v155 offset:1312
	ds_read_b64_tr_b16 v[62:63], v156 offset:40160
	ds_read_b64_tr_b16 v[60:61], v156 offset:38944
	v_pk_mul_f32 v[66:67], v[98:99], v[66:67]
	v_pk_mul_f32 v[64:65], v[108:109], v[64:65]
	v_pk_mul_f32 v[70:71], v[98:99], v[70:71]
	v_pk_mul_f32 v[68:69], v[108:109], v[68:69]
	s_waitcnt lgkmcnt(5)
	v_mfma_f32_16x16x32_bf16 v[48:51], v[32:35], v[56:59], v[48:51]
	s_min_u32 s12, s26, 29
	s_add_i32 s30, s12, 1
	s_sub_i32 s12, 30, s12
	s_waitcnt lgkmcnt(0)
	v_mfma_f32_16x16x32_bf16 v[32:35], v[32:35], v[60:63], v[52:55]
	s_and_b64 s[28:29], s[2:3], exec
	s_cselect_b32 s12, s30, s12
	s_lshl_b32 s12, s12, 7
	v_pk_mul_f32 v[54:55], v[98:99], v[74:75]
	v_pk_mul_f32 v[52:53], v[108:109], v[72:73]
	v_mfma_f32_16x16x32_bf16 v[64:67], v[36:39], v[56:59], v[64:67]
	v_mul_f32_e64 v74, v98, v78
	v_mul_f32_e64 v75, v99, v79
	v_pk_mul_f32 v[72:73], v[108:109], v[76:77]
	v_pk_mul_f32 v[78:79], v[98:99], v[82:83]
	v_mfma_f32_16x16x32_bf16 v[36:39], v[36:39], v[60:63], v[68:71]
	v_mul_f32_e64 v76, v108, v80
	v_mul_f32_e64 v77, v109, v81
	s_add_i32 s12, s12, s16
	s_mulk_i32 s12, 0x1c00
	v_lshl_add_u64 v[234:235], v[112:113], 0, s[12:13]
	v_lshl_add_u64 v[236:237], v[234:235], 0, s[4:5]
	v_lshl_add_u64 v[238:239], v[234:235], 0, s[8:9]
	v_lshl_add_u64 v[252:253], v[234:235], 0, s[10:11]
	global_load_dwordx4 v[202:205], v[234:235], off offset:1024
	global_load_dwordx4 v[206:209], v[234:235], off offset:2048
	global_load_dwordx4 v[210:213], v[236:237], off offset:1024
	global_load_dwordx4 v[214:217], v[236:237], off offset:2048
	global_load_dwordx4 v[218:221], v[238:239], off offset:1024
	global_load_dwordx4 v[222:225], v[238:239], off offset:2048
	global_load_dwordx4 v[226:229], v[252:253], off offset:1024
	global_load_dwordx4 v[230:233], v[252:253], off offset:2048
	v_pk_mul_f32 v[70:71], v[98:99], v[86:87]
	v_pk_mul_f32 v[68:69], v[108:109], v[84:85]
	v_mfma_f32_16x16x32_bf16 v[52:55], v[40:43], v[56:59], v[52:55]
	ds_read_b64_tr_b16 v[80:81], v155 offset:9728
	ds_read_b64_tr_b16 v[84:85], v155 offset:9760
	ds_read_b64_tr_b16 v[88:89], v155 offset:9792
	ds_read_b64_tr_b16 v[82:83], v155 offset:10944
	ds_read_b64_tr_b16 v[86:87], v155 offset:10976
	ds_read_b64_tr_b16 v[90:91], v155 offset:11008
	s_and_b64 s[28:29], s[2:3], exec
	v_mfma_f32_16x16x32_bf16 v[40:43], v[40:43], v[60:63], v[72:75]
	v_mfma_f32_16x16x32_bf16 v[56:59], v[44:47], v[56:59], v[76:79]
	s_nop 1
	ds_read_b64_tr_b16 v[72:73], v155 offset:9824
	ds_read_b64_tr_b16 v[76:77], v156 offset:48640
	ds_read_b64_tr_b16 v[78:79], v156 offset:49856
	v_mfma_f32_16x16x32_bf16 v[44:47], v[44:47], v[60:63], v[68:71]
	ds_read_b64_tr_b16 v[74:75], v155 offset:11040
	ds_read_b64_tr_b16 v[62:63], v156 offset:49888
	ds_read_b64_tr_b16 v[60:61], v156 offset:48672
	s_waitcnt vmcnt(22)
	v_lshlrev_b32_e32 v242, 16, v174
	v_and_b32_e32 v243, 0xffff0000, v174
	v_lshlrev_b32_e32 v244, 16, v175
	v_and_b32_e32 v245, 0xffff0000, v175
	v_lshlrev_b32_e32 v246, 16, v176
	v_and_b32_e32 v247, 0xffff0000, v176
	v_lshlrev_b32_e32 v248, 16, v177
	v_and_b32_e32 v249, 0xffff0000, v177
	v_pk_mul_f32 v[242:243], v[100:101], v[242:243]
	v_pk_mul_f32 v[244:245], v[100:101], v[244:245]
	v_pk_mul_f32 v[246:247], v[100:101], v[246:247]
	v_pk_mul_f32 v[248:249], v[100:101], v[248:249]
	v_cvt_pk_bf16_f32 v174, v242, v243
	v_cvt_pk_bf16_f32 v175, v244, v245
	v_cvt_pk_bf16_f32 v176, v246, v247
	v_cvt_pk_bf16_f32 v177, v248, v249
	ds_write_b128 v125, v[170:173]
	ds_write_b128 v126, v[174:177]
	s_waitcnt lgkmcnt(5)
	v_mfma_f32_16x16x32_bf16 v[48:51], v[80:83], v[76:79], v[48:51]
	s_waitcnt lgkmcnt(0)
	v_mfma_f32_16x16x32_bf16 v[32:35], v[80:83], v[60:63], v[32:35]
	v_mfma_f32_16x16x32_bf16 v[64:67], v[84:87], v[76:79], v[64:67]
	v_mfma_f32_16x16x32_bf16 v[36:39], v[84:87], v[60:63], v[36:39]
	ds_read_b64_tr_b16 v[68:69], v155 offset:19456
	ds_read_b64_tr_b16 v[80:81], v155 offset:19488
	ds_read_b64_tr_b16 v[84:85], v155 offset:19520
	ds_read_b64_tr_b16 v[70:71], v155 offset:20672
	ds_read_b64_tr_b16 v[82:83], v155 offset:20704
	ds_read_b64_tr_b16 v[86:87], v155 offset:20736
	v_mfma_f32_16x16x32_bf16 v[52:55], v[88:91], v[76:79], v[52:55]
	v_mfma_f32_16x16x32_bf16 v[40:43], v[88:91], v[60:63], v[40:43]
	v_mfma_f32_16x16x32_bf16 v[56:59], v[72:75], v[76:79], v[56:59]
	ds_read_b64_tr_b16 v[76:77], v155 offset:19552
	ds_read_b64_tr_b16 v[88:89], v156 offset:58368
	ds_read_b64_tr_b16 v[90:91], v156 offset:59584
	v_mfma_f32_16x16x32_bf16 v[44:47], v[72:75], v[60:63], v[44:47]
	ds_read_b64_tr_b16 v[78:79], v155 offset:20768
	ds_read_b64_tr_b16 v[62:63], v156 offset:59616
	ds_read_b64_tr_b16 v[60:61], v156 offset:58400
	s_waitcnt vmcnt(20)
	v_lshlrev_b32_e32 v242, 16, v182
	v_and_b32_e32 v243, 0xffff0000, v182
	v_lshlrev_b32_e32 v244, 16, v183
	v_and_b32_e32 v245, 0xffff0000, v183
	v_lshlrev_b32_e32 v246, 16, v184
	v_and_b32_e32 v247, 0xffff0000, v184
	v_lshlrev_b32_e32 v248, 16, v185
	v_and_b32_e32 v249, 0xffff0000, v185
	v_pk_mul_f32 v[242:243], v[102:103], v[242:243]
	v_pk_mul_f32 v[244:245], v[102:103], v[244:245]
	v_pk_mul_f32 v[246:247], v[102:103], v[246:247]
	v_pk_mul_f32 v[248:249], v[102:103], v[248:249]
	v_cvt_pk_bf16_f32 v182, v242, v243
	v_cvt_pk_bf16_f32 v183, v244, v245
	v_cvt_pk_bf16_f32 v184, v246, v247
	v_cvt_pk_bf16_f32 v185, v248, v249
	ds_write_b128 v125, v[178:181] offset:9728
	ds_write_b128 v126, v[182:185] offset:9728
	s_waitcnt lgkmcnt(5)
	v_mfma_f32_16x16x32_bf16 v[72:75], v[80:83], v[88:91], v[64:67]
	s_waitcnt lgkmcnt(0)
	v_mfma_f32_16x16x32_bf16 v[80:83], v[80:83], v[60:63], v[36:39]
	s_nop 2
	ds_read_b64_tr_b16 v[36:37], v155 offset:29184
	ds_read_b64_tr_b16 v[38:39], v155 offset:30400
	ds_read_b64_tr_b16 v[132:133], v155 offset:30432
	ds_read_b64_tr_b16 v[130:131], v155 offset:29216
	ds_read_b64_tr_b16 v[138:139], v155 offset:29248
	ds_read_b64_tr_b16 v[142:143], v155 offset:29280
	ds_read_b64_tr_b16 v[140:141], v155 offset:30464
	ds_read_b64_tr_b16 v[144:145], v155 offset:30496
	ds_read_b64_tr_b16 v[148:149], v122 offset:40128
	ds_read_b64_tr_b16 v[146:147], v122 offset:38912
	ds_read_b64_tr_b16 v[152:153], v122 offset:40160
	ds_read_b64_tr_b16 v[150:151], v122 offset:38944
	v_mfma_f32_16x16x32_bf16 v[48:51], v[68:71], v[88:91], v[48:51]
	v_mfma_f32_16x16x32_bf16 v[68:71], v[68:71], v[60:63], v[32:35]
	v_mfma_f32_16x16x32_bf16 v[134:137], v[84:87], v[88:91], v[52:55]
	v_mfma_f32_16x16x32_bf16 v[84:87], v[84:87], v[60:63], v[40:43]
	s_nop 2
	v_mfma_f32_16x16x32_bf16 v[154:157], v[76:79], v[60:63], v[44:47]
	v_mfma_f32_16x16x32_bf16 v[88:91], v[76:79], v[88:91], v[56:59]
	s_cselect_b32 s12, s26, s24
	s_add_i32 s12, s12, s17
	s_lshl_b64 s[28:29], s[12:13], 15
	s_waitcnt vmcnt(18)
	v_lshlrev_b32_e32 v242, 16, v190
	v_and_b32_e32 v243, 0xffff0000, v190
	v_lshlrev_b32_e32 v244, 16, v191
	v_and_b32_e32 v245, 0xffff0000, v191
	v_lshlrev_b32_e32 v246, 16, v192
	v_and_b32_e32 v247, 0xffff0000, v192
	v_lshlrev_b32_e32 v248, 16, v193
	v_and_b32_e32 v249, 0xffff0000, v193
	v_pk_mul_f32 v[242:243], v[104:105], v[242:243]
	v_pk_mul_f32 v[244:245], v[104:105], v[244:245]
	v_pk_mul_f32 v[246:247], v[104:105], v[246:247]
	v_pk_mul_f32 v[248:249], v[104:105], v[248:249]
	v_cvt_pk_bf16_f32 v190, v242, v243
	v_cvt_pk_bf16_f32 v191, v244, v245
	v_cvt_pk_bf16_f32 v192, v246, v247
	v_cvt_pk_bf16_f32 v193, v248, v249
	ds_write_b128 v125, v[186:189] offset:19456
	ds_write_b128 v126, v[190:193] offset:19456
	s_waitcnt lgkmcnt(4)
	v_mfma_f32_16x16x32_bf16 v[92:95], v[36:39], v[146:149], v[48:51]
	s_waitcnt vmcnt(16)
	v_lshlrev_b32_e32 v242, 16, v198
	v_and_b32_e32 v243, 0xffff0000, v198
	v_lshlrev_b32_e32 v244, 16, v199
	v_and_b32_e32 v245, 0xffff0000, v199
	v_lshlrev_b32_e32 v246, 16, v200
	v_and_b32_e32 v247, 0xffff0000, v200
	v_lshlrev_b32_e32 v248, 16, v201
	v_and_b32_e32 v249, 0xffff0000, v201
	v_pk_mul_f32 v[242:243], v[106:107], v[242:243]
	v_pk_mul_f32 v[244:245], v[106:107], v[244:245]
	v_pk_mul_f32 v[246:247], v[106:107], v[246:247]
	v_pk_mul_f32 v[248:249], v[106:107], v[248:249]
	v_cvt_pk_bf16_f32 v198, v242, v243
	v_cvt_pk_bf16_f32 v199, v244, v245
	v_cvt_pk_bf16_f32 v200, v246, v247
	v_cvt_pk_bf16_f32 v201, v248, v249
	ds_write_b128 v125, v[194:197] offset:29184
	ds_write_b128 v126, v[198:201] offset:29184
	s_waitcnt lgkmcnt(2)
	v_mfma_f32_16x16x32_bf16 v[64:67], v[36:39], v[150:153], v[68:71]
	s_nop 0
	s_nop 0
	s_nop 0
	v_mfma_f32_16x16x32_bf16 v[68:71], v[130:133], v[146:149], v[72:75]
	v_mfma_f32_16x16x32_bf16 v[72:75], v[130:133], v[150:153], v[80:83]
	v_lshl_add_u64 v[130:131], v[110:111], 0, s[28:29]
	v_lshl_add_u64 v[132:133], v[130:131], 0, v[96:97]
	v_mfma_f32_16x16x32_bf16 v[76:79], v[138:141], v[146:149], v[134:137]
	v_mfma_f32_16x16x32_bf16 v[80:83], v[138:141], v[150:153], v[84:87]
	s_nop 1
	v_add_co_u32_e32 v136, vcc, s25, v132
	v_cvt_pk_bf16_f32 v138, v92, v93
	v_mfma_f32_16x16x32_bf16 v[84:87], v[142:145], v[146:149], v[88:91]
	v_cvt_pk_bf16_f32 v139, v94, v95
	v_lshl_add_u64 v[134:135], v[130:131], 0, v[114:115]
	v_lshl_add_u64 v[130:131], v[130:131], 0, v[116:117]
	v_mfma_f32_16x16x32_bf16 v[88:91], v[142:145], v[150:153], v[154:157]
	v_addc_co_u32_e32 v137, vcc, 0, v133, vcc
	v_cvt_pk_bf16_f32 v140, v64, v65
	v_cvt_pk_bf16_f32 v141, v66, v67
	v_cvt_pk_bf16_f32 v142, v68, v69
	v_cvt_pk_bf16_f32 v143, v70, v71
	v_cvt_pk_bf16_f32 v144, v72, v73
	v_cvt_pk_bf16_f32 v145, v74, v75
	v_cvt_pk_bf16_f32 v146, v76, v77
	v_cvt_pk_bf16_f32 v147, v78, v79
	v_cvt_pk_bf16_f32 v148, v80, v81
	v_cvt_pk_bf16_f32 v149, v82, v83
	v_cvt_pk_bf16_f32 v150, v84, v85
	v_cvt_pk_bf16_f32 v151, v86, v87
	v_cvt_pk_bf16_f32 v152, v88, v89
	v_cvt_pk_bf16_f32 v153, v90, v91
	global_store_dwordx2 v[132:133], v[138:139], off
	global_store_dwordx2 v[136:137], v[140:141], off
	global_store_dwordx2 v[132:133], v[142:143], off offset:512
	global_store_dwordx2 v[134:135], v[144:145], off
	global_store_dwordx2 v[132:133], v[146:147], off offset:1024
	global_store_dwordx2 v[136:137], v[148:149], off offset:1024
	global_store_dwordx2 v[132:133], v[150:151], off offset:1536
	global_store_dwordx2 v[130:131], v[152:153], off
	s_add_i32 s24, s24, -2
	s_and_b64 vcc, exec, s[14:15]
	s_mov_b32 s26, s27
	s_cbranch_vccnz .LBB0_503
	s_waitcnt lgkmcnt(0)
	s_barrier

	.amdhsa_kernel _Z10fwd_kernel6Paramsiii
		.amdhsa_group_segment_fixed_size 0
		.amdhsa_private_segment_fixed_size 0
		.amdhsa_kernarg_size 504
		.amdhsa_user_sgpr_count 2
		.amdhsa_user_sgpr_dispatch_ptr 0
		.amdhsa_user_sgpr_queue_ptr 0
		.amdhsa_user_sgpr_kernarg_segment_ptr 1
		.amdhsa_user_sgpr_dispatch_id 0
		.amdhsa_user_sgpr_kernarg_preload_length 0
		.amdhsa_user_sgpr_kernarg_preload_offset 0
		.amdhsa_user_sgpr_private_segment_size 0
		.amdhsa_uses_dynamic_stack 0
		.amdhsa_enable_private_segment 0
		.amdhsa_system_sgpr_workgroup_id_x 1
		.amdhsa_system_sgpr_workgroup_id_y 0
		.amdhsa_system_sgpr_workgroup_id_z 0
		.amdhsa_system_sgpr_workgroup_info 0
		.amdhsa_system_vgpr_workitem_id 2
		.amdhsa_next_free_vgpr 256
		.amdhsa_next_free_sgpr 98
		.amdhsa_accum_offset 256
		.amdhsa_reserve_vcc 1
		.amdhsa_float_round_mode_32 0
		.amdhsa_float_round_mode_16_64 0
		.amdhsa_float_denorm_mode_32 3
		.amdhsa_float_denorm_mode_16_64 3
		.amdhsa_dx10_clamp 1
		.amdhsa_ieee_mode 1
		.amdhsa_fp16_overflow 0
		.amdhsa_tg_split 0
		.amdhsa_exception_fp_ieee_invalid_op 0
		.amdhsa_exception_fp_denorm_src 0
		.amdhsa_exception_fp_ieee_div_zero 0
		.amdhsa_exception_fp_ieee_overflow 0
		.amdhsa_exception_fp_ieee_underflow 0
		.amdhsa_exception_fp_ieee_inexact 0
		.amdhsa_exception_int_div_zero 0
	.end_amdhsa_kernel

amdhsa.kernels:
  - .agpr_count:     0
    .args:
      - .offset:         0
        .size:           232
        .value_kind:     by_value
      - .offset:         232
        .size:           4
        .value_kind:     by_value
      - .offset:         236
        .size:           4
        .value_kind:     by_value
      - .offset:         240
        .size:           4
        .value_kind:     by_value
      - .offset:         248
        .size:           4
        .value_kind:     hidden_block_count_x
      - .offset:         252
        .size:           4
        .value_kind:     hidden_block_count_y
      - .offset:         256
        .size:           4
        .value_kind:     hidden_block_count_z
      - .offset:         260
        .size:           2
        .value_kind:     hidden_group_size_x
      - .offset:         262
        .size:           2
        .value_kind:     hidden_group_size_y
      - .offset:         264
        .size:           2
        .value_kind:     hidden_group_size_z
      - .offset:         266
        .size:           2
        .value_kind:     hidden_remainder_x
      - .offset:         268
        .size:           2
        .value_kind:     hidden_remainder_y
      - .offset:         270
        .size:           2
        .value_kind:     hidden_remainder_z
      - .offset:         288
        .size:           8
        .value_kind:     hidden_global_offset_x
      - .offset:         296
        .size:           8
        .value_kind:     hidden_global_offset_y
      - .offset:         304
        .size:           8
        .value_kind:     hidden_global_offset_z
      - .offset:         312
        .size:           2
        .value_kind:     hidden_grid_dims
      - .offset:         336
        .size:           8
        .value_kind:     hidden_multigrid_sync_arg
      - .offset:         368
        .size:           4
        .value_kind:     hidden_dynamic_lds_size
    .group_segment_fixed_size: 0
    .kernarg_segment_align: 8
    .kernarg_segment_size: 504
    .language:       OpenCL C
    .language_version:
      - 2
      - 0
    .max_flat_workgroup_size: 512
    .name:           _Z10fwd_kernel6Paramsiii
    .private_segment_fixed_size: 0
    .sgpr_count:     104
    .sgpr_spill_count: 42
    .symbol:         _Z10fwd_kernel6Paramsiii.kd
    .uniform_work_group_size: 1
    .uses_dynamic_stack: false
    .vgpr_count:     256
    .vgpr_spill_count: 0
    .wavefront_size: 64
